# attention combine epilogue: 16 row-strided 8-byte YATT stores per lane widened to 8 16-byte stores via v_permlane32_swap (same values)
# speedup vs baseline: 1.0150x; 1.0045x over previous
; __device__ __forceinline__ void attn_unit(const bf16* __restrict__ QB, const bf16* __restrict__ KB, const bf16* __restrict__ VB, bf16* __restrict__ YATT, ...
;     ...
;         __syncthreads();
;         if (jc == 1) {
;             float ss = 0.f;
; #pragma unroll
;             for (int e = 0; e < 4; ++e)
; #pragma unroll
;                 for (int i = 0; i < 8; ++i) { const unsigned w = stash[(e * 8 + i) * 256];
;                     const float o0 = bflo(w) - lam * (acc[e][2 * i] * inv), o1 = bfhi(w) - lam * (acc[e][2 * i + 1] * inv);
;                     acc[e][2 * i] = o0; acc[e][2 * i + 1] = o1; ss += o0 * o0 + o1 * o1; }
.LBB0_585:
	s_cmp_lg_u32 s38, 1
	s_waitcnt lgkmcnt(0)
	s_barrier
	s_cbranch_scc1 .LBB0_556
	ds_read2st64_b32 v[2:3], v6 offset1:4
	v_pk_mul_f32 v[8:9], v[66:67], v[4:5] op_sel_hi:[1,0]
	ds_read2st64_b32 v[14:15], v6 offset0:8 offset1:12
	v_pk_mul_f32 v[16:17], v[70:71], v[4:5] op_sel_hi:[1,0]
	ds_read2st64_b32 v[66:67], v6 offset0:16 offset1:20
	s_waitcnt lgkmcnt(2)
	v_lshlrev_b32_e32 v10, 16, v2
	v_and_b32_e32 v11, 0xffff0000, v2
	v_lshlrev_b32_e32 v12, 16, v3
	v_and_b32_e32 v13, 0xffff0000, v3
	v_pk_fma_f32 v[2:3], v[176:177], v[8:9], v[10:11] neg_lo:[1,0,0] neg_hi:[1,0,0]
	v_pk_mul_f32 v[10:11], v[68:69], v[4:5] op_sel_hi:[1,0]
	v_mul_f32_e32 v8, v3, v3
	v_pk_fma_f32 v[10:11], v[176:177], v[10:11], v[12:13] neg_lo:[1,0,0] neg_hi:[1,0,0]
	v_pk_fma_f32 v[8:9], v[2:3], v[2:3], v[8:9] op_sel_hi:[1,1,0]
	v_mul_f32_e32 v12, v11, v11
	v_pk_fma_f32 v[12:13], v[10:11], v[10:11], v[12:13] op_sel_hi:[1,1,0]
	v_pk_mul_f32 v[68:69], v[74:75], v[4:5] op_sel_hi:[1,0]
	v_pk_add_f32 v[8:9], v[8:9], v[12:13]
	s_waitcnt lgkmcnt(1)
	v_lshlrev_b32_e32 v12, 16, v14
	v_and_b32_e32 v13, 0xffff0000, v14
	v_pk_fma_f32 v[12:13], v[176:177], v[16:17], v[12:13] neg_lo:[1,0,0] neg_hi:[1,0,0]
	ds_read2st64_b32 v[70:71], v6 offset0:24 offset1:28
	v_mul_f32_e32 v14, v13, v13
	v_pk_fma_f32 v[16:17], v[12:13], v[12:13], v[14:15] op_sel_hi:[1,1,0]
	v_lshlrev_b32_e32 v14, 16, v15
	v_pk_add_f32 v[8:9], v[8:9], v[16:17]
	v_and_b32_e32 v15, 0xffff0000, v15
	v_pk_mul_f32 v[16:17], v[72:73], v[4:5] op_sel_hi:[1,0]
	v_pk_mul_f32 v[72:73], v[78:79], v[4:5] op_sel_hi:[1,0]
	v_pk_fma_f32 v[14:15], v[176:177], v[16:17], v[14:15] neg_lo:[1,0,0] neg_hi:[1,0,0]
	ds_read2st64_b32 v[74:75], v6 offset0:32 offset1:36
	v_mul_f32_e32 v16, v15, v15
	v_pk_fma_f32 v[16:17], v[14:15], v[14:15], v[16:17] op_sel_hi:[1,1,0]
	v_pk_mul_f32 v[50:51], v[50:51], v[4:5] op_sel_hi:[1,0]
	v_pk_add_f32 v[8:9], v[8:9], v[16:17]
	s_waitcnt lgkmcnt(2)
	v_lshlrev_b32_e32 v16, 16, v66
	v_and_b32_e32 v17, 0xffff0000, v66
	v_pk_fma_f32 v[16:17], v[176:177], v[68:69], v[16:17] neg_lo:[1,0,0] neg_hi:[1,0,0]
	v_pk_mul_f32 v[52:53], v[52:53], v[4:5] op_sel_hi:[1,0]
	v_mul_f32_e32 v66, v17, v17
	v_pk_fma_f32 v[68:69], v[16:17], v[16:17], v[66:67] op_sel_hi:[1,1,0]
	v_lshlrev_b32_e32 v66, 16, v67
	v_pk_add_f32 v[8:9], v[8:9], v[68:69]
	v_and_b32_e32 v67, 0xffff0000, v67
	v_pk_mul_f32 v[68:69], v[76:77], v[4:5] op_sel_hi:[1,0]
	v_pk_mul_f32 v[54:55], v[54:55], v[4:5] op_sel_hi:[1,0]
	v_pk_fma_f32 v[66:67], v[176:177], v[68:69], v[66:67] neg_lo:[1,0,0] neg_hi:[1,0,0]
	v_pk_mul_f32 v[56:57], v[56:57], v[4:5] op_sel_hi:[1,0]
	v_mul_f32_e32 v68, v67, v67
	v_pk_fma_f32 v[68:69], v[66:67], v[66:67], v[68:69] op_sel_hi:[1,1,0]
	v_pk_mul_f32 v[58:59], v[58:59], v[4:5] op_sel_hi:[1,0]
	v_pk_add_f32 v[8:9], v[8:9], v[68:69]
	s_waitcnt lgkmcnt(1)
	v_lshlrev_b32_e32 v68, 16, v70
	v_and_b32_e32 v69, 0xffff0000, v70
	v_pk_fma_f32 v[68:69], v[176:177], v[72:73], v[68:69] neg_lo:[1,0,0] neg_hi:[1,0,0]
	ds_read2st64_b32 v[76:77], v6 offset0:56 offset1:60
	v_mul_f32_e32 v70, v69, v69
	v_pk_fma_f32 v[72:73], v[68:69], v[68:69], v[70:71] op_sel_hi:[1,1,0]
	v_lshlrev_b32_e32 v70, 16, v71
	v_pk_add_f32 v[8:9], v[8:9], v[72:73]
	v_and_b32_e32 v71, 0xffff0000, v71
	v_pk_mul_f32 v[72:73], v[80:81], v[4:5] op_sel_hi:[1,0]
	v_pk_mul_f32 v[60:61], v[60:61], v[4:5] op_sel_hi:[1,0]
	v_pk_fma_f32 v[70:71], v[176:177], v[72:73], v[70:71] neg_lo:[1,0,0] neg_hi:[1,0,0]
	v_pk_mul_f32 v[34:35], v[34:35], v[4:5] op_sel_hi:[1,0]
	v_mul_f32_e32 v72, v71, v71
	v_pk_fma_f32 v[72:73], v[70:71], v[70:71], v[72:73] op_sel_hi:[1,1,0]
	v_pk_mul_f32 v[36:37], v[36:37], v[4:5] op_sel_hi:[1,0]
	v_pk_add_f32 v[8:9], v[8:9], v[72:73]
	s_waitcnt lgkmcnt(1)
	v_lshlrev_b32_e32 v72, 16, v74
	v_and_b32_e32 v73, 0xffff0000, v74
	v_pk_fma_f32 v[50:51], v[176:177], v[50:51], v[72:73] neg_lo:[1,0,0] neg_hi:[1,0,0]
	v_pk_mul_f32 v[38:39], v[38:39], v[4:5] op_sel_hi:[1,0]
	v_mul_f32_e32 v72, v51, v51
	v_pk_fma_f32 v[72:73], v[50:51], v[50:51], v[72:73] op_sel_hi:[1,1,0]
	v_pk_mul_f32 v[40:41], v[40:41], v[4:5] op_sel_hi:[1,0]
	v_pk_add_f32 v[8:9], v[8:9], v[72:73]
	v_lshlrev_b32_e32 v72, 16, v75
	v_and_b32_e32 v73, 0xffff0000, v75
	ds_read2st64_b32 v[74:75], v6 offset0:40 offset1:44
	v_pk_fma_f32 v[52:53], v[176:177], v[52:53], v[72:73] neg_lo:[1,0,0] neg_hi:[1,0,0]
	v_pk_mul_f32 v[42:43], v[42:43], v[4:5] op_sel_hi:[1,0]
	v_mul_f32_e32 v72, v53, v53
	v_pk_fma_f32 v[72:73], v[52:53], v[52:53], v[72:73] op_sel_hi:[1,1,0]
	v_pk_mul_f32 v[44:45], v[44:45], v[4:5] op_sel_hi:[1,0]
	v_pk_add_f32 v[8:9], v[8:9], v[72:73]
	s_waitcnt lgkmcnt(0)
	v_lshlrev_b32_e32 v72, 16, v74
	v_and_b32_e32 v73, 0xffff0000, v74
	v_pk_fma_f32 v[54:55], v[176:177], v[54:55], v[72:73] neg_lo:[1,0,0] neg_hi:[1,0,0]
	v_pk_mul_f32 v[46:47], v[46:47], v[4:5] op_sel_hi:[1,0]
	v_mul_f32_e32 v72, v55, v55
	v_pk_fma_f32 v[72:73], v[54:55], v[54:55], v[72:73] op_sel_hi:[1,1,0]
	v_pk_mul_f32 v[48:49], v[48:49], v[4:5] op_sel_hi:[1,0]
	v_pk_add_f32 v[8:9], v[8:9], v[72:73]
	v_lshlrev_b32_e32 v72, 16, v75
	v_and_b32_e32 v73, 0xffff0000, v75
	ds_read2st64_b32 v[74:75], v6 offset0:48 offset1:52
	v_pk_fma_f32 v[72:73], v[176:177], v[56:57], v[72:73] neg_lo:[1,0,0] neg_hi:[1,0,0]
	v_pk_mul_f32 v[18:19], v[18:19], v[4:5] op_sel_hi:[1,0]
	v_mul_f32_e32 v56, v73, v73
	v_pk_fma_f32 v[56:57], v[72:73], v[72:73], v[56:57] op_sel_hi:[1,1,0]
	v_pk_mul_f32 v[20:21], v[20:21], v[4:5] op_sel_hi:[1,0]
	v_pk_add_f32 v[8:9], v[8:9], v[56:57]
	s_waitcnt lgkmcnt(0)
; __device__ __forceinline__ void attn_unit(const bf16* __restrict__ QB, const bf16* __restrict__ KB, const bf16* __restrict__ VB, bf16* __restrict__ YATT, ...
;     ...
;         __syncthreads();
;         if (jc == 1) {
;             float ss = 0.f;
; #pragma unroll
;             for (int e = 0; e < 4; ++e)
; #pragma unroll
;                 for (int i = 0; i < 8; ++i) { const unsigned w = stash[(e * 8 + i) * 256];
;                     const float o0 = bflo(w) - lam * (acc[e][2 * i] * inv), o1 = bfhi(w) - lam * (acc[e][2 * i + 1] * inv);
;                     acc[e][2 * i] = o0; acc[e][2 * i + 1] = o1; ss += o0 * o0 + o1 * o1; }
	v_lshlrev_b32_e32 v56, 16, v74
	v_and_b32_e32 v57, 0xffff0000, v74
	v_pk_fma_f32 v[58:59], v[176:177], v[58:59], v[56:57] neg_lo:[1,0,0] neg_hi:[1,0,0]
	v_pk_mul_f32 v[22:23], v[22:23], v[4:5] op_sel_hi:[1,0]
	v_mul_f32_e32 v56, v59, v59
	v_pk_fma_f32 v[56:57], v[58:59], v[58:59], v[56:57] op_sel_hi:[1,1,0]
	v_pk_mul_f32 v[24:25], v[24:25], v[4:5] op_sel_hi:[1,0]
	v_pk_add_f32 v[8:9], v[8:9], v[56:57]
	v_lshlrev_b32_e32 v56, 16, v75
	v_and_b32_e32 v57, 0xffff0000, v75
	v_pk_fma_f32 v[74:75], v[176:177], v[60:61], v[56:57] neg_lo:[1,0,0] neg_hi:[1,0,0]
	v_pk_mul_f32 v[60:61], v[62:63], v[4:5] op_sel_hi:[1,0]
	v_mul_f32_e32 v56, v75, v75
	v_pk_fma_f32 v[56:57], v[74:75], v[74:75], v[56:57] op_sel_hi:[1,1,0]
	v_pk_mul_f32 v[62:63], v[64:65], v[4:5] op_sel_hi:[1,0]
	v_pk_add_f32 v[8:9], v[8:9], v[56:57]
	v_lshlrev_b32_e32 v56, 16, v76
	v_and_b32_e32 v57, 0xffff0000, v76
	v_pk_fma_f32 v[56:57], v[176:177], v[60:61], v[56:57] neg_lo:[1,0,0] neg_hi:[1,0,0]
	ds_read2st64_b32 v[64:65], v6 offset0:64 offset1:68
	v_mul_f32_e32 v60, v57, v57
	v_pk_fma_f32 v[60:61], v[56:57], v[56:57], v[60:61] op_sel_hi:[1,1,0]
	v_pk_mul_f32 v[26:27], v[26:27], v[4:5] op_sel_hi:[1,0]
	v_pk_add_f32 v[8:9], v[8:9], v[60:61]
	v_lshlrev_b32_e32 v60, 16, v77
	v_and_b32_e32 v61, 0xffff0000, v77
	v_pk_fma_f32 v[60:61], v[176:177], v[62:63], v[60:61] neg_lo:[1,0,0] neg_hi:[1,0,0]
	v_pk_mul_f32 v[28:29], v[28:29], v[4:5] op_sel_hi:[1,0]
	v_mul_f32_e32 v62, v61, v61
	v_pk_fma_f32 v[62:63], v[60:61], v[60:61], v[62:63] op_sel_hi:[1,1,0]
	v_pk_mul_f32 v[30:31], v[30:31], v[4:5] op_sel_hi:[1,0]
	v_pk_add_f32 v[8:9], v[8:9], v[62:63]
	s_waitcnt lgkmcnt(0)
	v_lshlrev_b32_e32 v62, 16, v64
	v_and_b32_e32 v63, 0xffff0000, v64
	v_pk_fma_f32 v[34:35], v[176:177], v[34:35], v[62:63] neg_lo:[1,0,0] neg_hi:[1,0,0]
	v_pk_mul_f32 v[32:33], v[32:33], v[4:5] op_sel_hi:[1,0]
	v_mul_f32_e32 v62, v35, v35
	v_pk_fma_f32 v[62:63], v[34:35], v[34:35], v[62:63] op_sel_hi:[1,1,0]
	s_nop 0
	v_pk_add_f32 v[8:9], v[8:9], v[62:63]
	v_lshlrev_b32_e32 v62, 16, v65
	v_and_b32_e32 v63, 0xffff0000, v65
	ds_read2st64_b32 v[64:65], v6 offset0:72 offset1:76
	v_pk_fma_f32 v[36:37], v[176:177], v[36:37], v[62:63] neg_lo:[1,0,0] neg_hi:[1,0,0]
	s_nop 0
	v_mul_f32_e32 v62, v37, v37
	v_pk_fma_f32 v[62:63], v[36:37], v[36:37], v[62:63] op_sel_hi:[1,1,0]
	s_nop 0
	v_pk_add_f32 v[8:9], v[8:9], v[62:63]
	s_waitcnt lgkmcnt(0)
	v_lshlrev_b32_e32 v62, 16, v64
	v_and_b32_e32 v63, 0xffff0000, v64
	v_pk_fma_f32 v[38:39], v[176:177], v[38:39], v[62:63] neg_lo:[1,0,0] neg_hi:[1,0,0]
	s_nop 0
	v_mul_f32_e32 v62, v39, v39
	v_pk_fma_f32 v[62:63], v[38:39], v[38:39], v[62:63] op_sel_hi:[1,1,0]
	s_nop 0
	v_pk_add_f32 v[8:9], v[8:9], v[62:63]
	v_lshlrev_b32_e32 v62, 16, v65
	v_and_b32_e32 v63, 0xffff0000, v65
	ds_read2st64_b32 v[64:65], v6 offset0:80 offset1:84
	v_pk_fma_f32 v[40:41], v[176:177], v[40:41], v[62:63] neg_lo:[1,0,0] neg_hi:[1,0,0]
	s_nop 0
	v_mul_f32_e32 v62, v41, v41
	v_pk_fma_f32 v[62:63], v[40:41], v[40:41], v[62:63] op_sel_hi:[1,1,0]
	s_nop 0
	v_pk_add_f32 v[8:9], v[8:9], v[62:63]
	s_waitcnt lgkmcnt(0)
	v_lshlrev_b32_e32 v62, 16, v64
	v_and_b32_e32 v63, 0xffff0000, v64
	v_pk_fma_f32 v[42:43], v[176:177], v[42:43], v[62:63] neg_lo:[1,0,0] neg_hi:[1,0,0]
	s_nop 0
	v_mul_f32_e32 v62, v43, v43
	v_pk_fma_f32 v[62:63], v[42:43], v[42:43], v[62:63] op_sel_hi:[1,1,0]
	s_nop 0
	v_pk_add_f32 v[8:9], v[8:9], v[62:63]
	v_lshlrev_b32_e32 v62, 16, v65
	v_and_b32_e32 v63, 0xffff0000, v65
	ds_read2st64_b32 v[64:65], v6 offset0:88 offset1:92
	v_pk_fma_f32 v[44:45], v[176:177], v[44:45], v[62:63] neg_lo:[1,0,0] neg_hi:[1,0,0]
	s_nop 0
	v_mul_f32_e32 v62, v45, v45
	v_pk_fma_f32 v[62:63], v[44:45], v[44:45], v[62:63] op_sel_hi:[1,1,0]
	s_nop 0
	v_pk_add_f32 v[8:9], v[8:9], v[62:63]
	s_waitcnt lgkmcnt(0)
	v_lshlrev_b32_e32 v62, 16, v64
	v_and_b32_e32 v63, 0xffff0000, v64
	v_pk_fma_f32 v[46:47], v[176:177], v[46:47], v[62:63] neg_lo:[1,0,0] neg_hi:[1,0,0]
	s_nop 0
	v_mul_f32_e32 v62, v47, v47
	v_pk_fma_f32 v[62:63], v[46:47], v[46:47], v[62:63] op_sel_hi:[1,1,0]
	s_nop 0
	v_pk_add_f32 v[8:9], v[8:9], v[62:63]
	v_lshlrev_b32_e32 v62, 16, v65
	v_and_b32_e32 v63, 0xffff0000, v65
	ds_read2st64_b32 v[64:65], v6 offset0:96 offset1:100
	v_pk_fma_f32 v[48:49], v[176:177], v[48:49], v[62:63] neg_lo:[1,0,0] neg_hi:[1,0,0]
	s_nop 0
	v_mul_f32_e32 v62, v49, v49
	v_pk_fma_f32 v[62:63], v[48:49], v[48:49], v[62:63] op_sel_hi:[1,1,0]
	s_nop 0
	v_pk_add_f32 v[8:9], v[8:9], v[62:63]
	s_waitcnt lgkmcnt(0)
	v_lshlrev_b32_e32 v62, 16, v64
	v_and_b32_e32 v63, 0xffff0000, v64
	v_pk_fma_f32 v[18:19], v[176:177], v[18:19], v[62:63] neg_lo:[1,0,0] neg_hi:[1,0,0]
	s_nop 0
	v_mul_f32_e32 v62, v19, v19
	v_pk_fma_f32 v[62:63], v[18:19], v[18:19], v[62:63] op_sel_hi:[1,1,0]
	s_nop 0
	v_pk_add_f32 v[8:9], v[8:9], v[62:63]
	v_lshlrev_b32_e32 v62, 16, v65
	v_and_b32_e32 v63, 0xffff0000, v65
	ds_read2st64_b32 v[64:65], v6 offset0:104 offset1:108
	v_pk_fma_f32 v[20:21], v[176:177], v[20:21], v[62:63] neg_lo:[1,0,0] neg_hi:[1,0,0]
	s_nop 0
	v_mul_f32_e32 v62, v21, v21
	v_pk_fma_f32 v[62:63], v[20:21], v[20:21], v[62:63] op_sel_hi:[1,1,0]
	s_nop 0
	v_pk_add_f32 v[8:9], v[8:9], v[62:63]
	s_waitcnt lgkmcnt(0)
	v_lshlrev_b32_e32 v62, 16, v64
	v_and_b32_e32 v63, 0xffff0000, v64
	v_pk_fma_f32 v[22:23], v[176:177], v[22:23], v[62:63] neg_lo:[1,0,0] neg_hi:[1,0,0]
	s_nop 0
	v_mul_f32_e32 v62, v23, v23
	v_pk_fma_f32 v[62:63], v[22:23], v[22:23], v[62:63] op_sel_hi:[1,1,0]
	s_nop 0
	v_pk_add_f32 v[8:9], v[8:9], v[62:63]
	v_lshlrev_b32_e32 v62, 16, v65
	v_and_b32_e32 v63, 0xffff0000, v65
	ds_read2st64_b32 v[64:65], v6 offset0:112 offset1:116
	v_pk_fma_f32 v[24:25], v[176:177], v[24:25], v[62:63] neg_lo:[1,0,0] neg_hi:[1,0,0]
	ds_read2st64_b32 v[6:7], v6 offset0:120 offset1:124
	v_mul_f32_e32 v62, v25, v25
	v_pk_fma_f32 v[62:63], v[24:25], v[24:25], v[62:63] op_sel_hi:[1,1,0]
	s_nop 0
	v_pk_add_f32 v[8:9], v[8:9], v[62:63]
	s_waitcnt lgkmcnt(1)
; __device__ __forceinline__ void attn_unit(const bf16* __restrict__ QB, const bf16* __restrict__ KB, const bf16* __restrict__ VB, bf16* __restrict__ YATT, ...
;     ...
;                 for (int i = 0; i < 8; ++i) { const unsigned w = stash[(e * 8 + i) * 256];
;                     const float o0 = bflo(w) - lam * (acc[e][2 * i] * inv), o1 = bfhi(w) - lam * (acc[e][2 * i + 1] * inv);
;                     acc[e][2 * i] = o0; acc[e][2 * i + 1] = o1; ss += o0 * o0 + o1 * o1; }
;             { auto rr = __builtin_amdgcn_permlane32_swap(__float_as_uint(ss), __float_as_uint(ss), false, false); ss = __uint_as_float(rr[0]) + __uint_as_float(rr[1]); }
;             const float rn = __builtin_amdgcn_rsqf(ss * (1.f / 128.f) + EPS) * 0.8f;
;             if (tq >= 0 && jmax >= 0) {
	v_lshlrev_b32_e32 v62, 16, v64
	v_and_b32_e32 v63, 0xffff0000, v64
	v_pk_fma_f32 v[26:27], v[176:177], v[26:27], v[62:63] neg_lo:[1,0,0] neg_hi:[1,0,0]
	s_nop 0
	v_mul_f32_e32 v62, v27, v27
	v_pk_fma_f32 v[62:63], v[26:27], v[26:27], v[62:63] op_sel_hi:[1,1,0]
	s_nop 0
	v_pk_add_f32 v[8:9], v[8:9], v[62:63]
	v_lshlrev_b32_e32 v62, 16, v65
	v_and_b32_e32 v63, 0xffff0000, v65
	v_pk_fma_f32 v[28:29], v[176:177], v[28:29], v[62:63] neg_lo:[1,0,0] neg_hi:[1,0,0]
	s_nop 0
	v_mul_f32_e32 v62, v29, v29
	v_pk_fma_f32 v[62:63], v[28:29], v[28:29], v[62:63] op_sel_hi:[1,1,0]
	s_nop 0
	v_pk_add_f32 v[8:9], v[8:9], v[62:63]
	s_waitcnt lgkmcnt(0)
	v_lshlrev_b32_e32 v62, 16, v6
	v_and_b32_e32 v63, 0xffff0000, v6
	v_pk_fma_f32 v[30:31], v[176:177], v[30:31], v[62:63] neg_lo:[1,0,0] neg_hi:[1,0,0]
	s_nop 0
	v_mul_f32_e32 v6, v31, v31
	v_pk_fma_f32 v[62:63], v[30:31], v[30:31], v[6:7] op_sel_hi:[1,1,0]
	v_lshlrev_b32_e32 v6, 16, v7
	v_and_b32_e32 v7, 0xffff0000, v7
	v_pk_fma_f32 v[32:33], v[176:177], v[32:33], v[6:7] neg_lo:[1,0,0] neg_hi:[1,0,0]
	v_pk_add_f32 v[8:9], v[8:9], v[62:63]
	v_mul_f32_e32 v4, v33, v33
	v_pk_fma_f32 v[6:7], v[32:33], v[32:33], v[4:5] op_sel_hi:[1,1,0]
	s_nop 0
	v_pk_add_f32 v[62:63], v[8:9], v[6:7]
	v_or_b32_e32 v6, s73, v194
	v_mov_b32_e32 v4, v62
	s_nop 1
	v_permlane32_swap_b32_e32 v62, v4
	v_cmp_lt_i32_e32 vcc, -1, v6
	s_waitcnt vmcnt(0)
	s_and_saveexec_b64 s[4:5], vcc
	s_cbranch_execz .LBB0_555
; __device__ __forceinline__ unsigned cvtpk(float lo, float hi) { f32x2 v = {lo, hi}; bf16x2_t b = __builtin_convertvector(v, bf16x2_t); return __builtin_bit_cast(unsigned, b); }
; __device__ __forceinline__ void attn_unit(const bf16* __restrict__ QB, const bf16* __restrict__ KB, const bf16* __restrict__ VB, bf16* __restrict__ YATT, ...
;     ...
;             if (tq >= 0 && jmax >= 0) {
;                 const int orow = tq < NMETA ? MAINR + tq : b * SEQ + tq - NMETA;
;                 bf16* op = YATT + (size_t)orow * 512 + h * 128 + 4 * hi;
; #pragma unroll
;                 for (int e = 0; e < 4; ++e)
; #pragma unroll
;                     for (int i = 0; i < 4; ++i) { const f32x4 g = *(const f32x4*)(sg + 32 * e + 8 * i + 4 * hi);
;                         u32x2 w; w.x = cvtpk(acc[e][4 * i] * rn * g[0], acc[e][4 * i + 1] * rn * g[1]); w.y = cvtpk(acc[e][4 * i + 2] * rn * g[2], acc[e][4 * i + 3] * rn * g[3]); *(u32x2*)(op + 32 * e + 8 * i) = w; }
;             }
	v_add_f32_e32 v4, v62, v4
	s_lshl_b32 s8, s72, 12
	v_fmamk_f32 v4, v4, 0x3c000000, v1
	s_add_i32 s8, s8, -16
	v_rsq_f32_e32 v134, v4
	v_mov_b32_e32 v4, s8
	v_cmp_lt_u32_e32 vcc, 15, v194
	s_mov_b64 s[6:7], 0x1af00000
	v_mul_f32_e32 v134, 0x3f4ccccd, v134
	v_cndmask_b32_e32 v4, v193, v4, vcc
	v_add_u32_e32 v4, v4, v194
	v_lshlrev_b64 v[132:133], 10, v[4:5]
	v_lshl_add_u64 v[132:133], s[88:89], 0, v[132:133]
	v_lshlrev_b32_e32 v4, 2, v179
	v_lshl_add_u64 v[132:133], v[132:133], 0, s[82:83]
	v_lshl_add_u64 v[132:133], v[132:133], 0, v[4:5]
	v_lshl_add_u64 v[136:137], v[132:133], 0, s[6:7]
	v_pk_mul_f32 v[80:81], v[2:3], v[134:135] op_sel_hi:[1,0]
	v_pk_mul_f32 v[82:83], v[10:11], v[134:135] op_sel_hi:[1,0]
	v_pk_mul_f32 v[62:63], v[12:13], v[134:135] op_sel_hi:[1,0]
	v_pk_mul_f32 v[64:65], v[14:15], v[134:135] op_sel_hi:[1,0]
	v_pk_mul_f32 v[80:81], v[80:81], v[140:141]
	v_pk_mul_f32 v[82:83], v[82:83], v[142:143]
	v_pk_mul_f32 v[62:63], v[62:63], v[144:145]
	v_pk_mul_f32 v[64:65], v[64:65], v[146:147]
	v_cvt_pk_bf16_f32 v76, v80, v81
	v_cvt_pk_bf16_f32 v77, v82, v83
	v_cvt_pk_bf16_f32 v78, v62, v63
	v_cvt_pk_bf16_f32 v79, v64, v65
	s_nop 1
	v_permlane32_swap_b32_e32 v76, v78
	v_permlane32_swap_b32_e32 v77, v79
	s_nop 0
	global_store_dwordx4 v[136:137], v[76:79], off offset:0
	v_pk_mul_f32 v[80:81], v[16:17], v[134:135] op_sel_hi:[1,0]
	v_pk_mul_f32 v[82:83], v[66:67], v[134:135] op_sel_hi:[1,0]
	v_pk_mul_f32 v[62:63], v[68:69], v[134:135] op_sel_hi:[1,0]
	v_pk_mul_f32 v[64:65], v[70:71], v[134:135] op_sel_hi:[1,0]
	v_pk_mul_f32 v[80:81], v[80:81], v[160:161]
	v_pk_mul_f32 v[82:83], v[82:83], v[162:163]
	v_pk_mul_f32 v[62:63], v[62:63], v[84:85]
	v_pk_mul_f32 v[64:65], v[64:65], v[86:87]
	v_cvt_pk_bf16_f32 v76, v80, v81
	v_cvt_pk_bf16_f32 v77, v82, v83
	v_cvt_pk_bf16_f32 v78, v62, v63
	v_cvt_pk_bf16_f32 v79, v64, v65
	s_nop 1
	v_permlane32_swap_b32_e32 v76, v78
	v_permlane32_swap_b32_e32 v77, v79
	s_nop 0
	global_store_dwordx4 v[136:137], v[76:79], off offset:32
	v_pk_mul_f32 v[80:81], v[50:51], v[134:135] op_sel_hi:[1,0]
	v_pk_mul_f32 v[82:83], v[52:53], v[134:135] op_sel_hi:[1,0]
	v_pk_mul_f32 v[62:63], v[54:55], v[134:135] op_sel_hi:[1,0]
	v_pk_mul_f32 v[64:65], v[72:73], v[134:135] op_sel_hi:[1,0]
	v_pk_mul_f32 v[80:81], v[80:81], v[88:89]
	v_pk_mul_f32 v[82:83], v[82:83], v[90:91]
	v_pk_mul_f32 v[62:63], v[62:63], v[92:93]
	v_pk_mul_f32 v[64:65], v[64:65], v[94:95]
	v_cvt_pk_bf16_f32 v76, v80, v81
	v_cvt_pk_bf16_f32 v77, v82, v83
	v_cvt_pk_bf16_f32 v78, v62, v63
	v_cvt_pk_bf16_f32 v79, v64, v65
	s_nop 1
	v_permlane32_swap_b32_e32 v76, v78
	v_permlane32_swap_b32_e32 v77, v79
	s_nop 0
	global_store_dwordx4 v[136:137], v[76:79], off offset:64
	v_pk_mul_f32 v[80:81], v[58:59], v[134:135] op_sel_hi:[1,0]
	v_pk_mul_f32 v[82:83], v[74:75], v[134:135] op_sel_hi:[1,0]
	v_pk_mul_f32 v[62:63], v[56:57], v[134:135] op_sel_hi:[1,0]
	v_pk_mul_f32 v[64:65], v[60:61], v[134:135] op_sel_hi:[1,0]
	v_pk_mul_f32 v[80:81], v[80:81], v[96:97]
	v_pk_mul_f32 v[82:83], v[82:83], v[98:99]
	v_pk_mul_f32 v[62:63], v[62:63], v[164:165]
	v_pk_mul_f32 v[64:65], v[64:65], v[166:167]
	v_cvt_pk_bf16_f32 v76, v80, v81
	v_cvt_pk_bf16_f32 v77, v82, v83
	v_cvt_pk_bf16_f32 v78, v62, v63
	v_cvt_pk_bf16_f32 v79, v64, v65
	s_nop 1
	v_permlane32_swap_b32_e32 v76, v78
	v_permlane32_swap_b32_e32 v77, v79
	s_nop 0
	global_store_dwordx4 v[136:137], v[76:79], off offset:96
	v_pk_mul_f32 v[80:81], v[34:35], v[134:135] op_sel_hi:[1,0]
	v_pk_mul_f32 v[82:83], v[36:37], v[134:135] op_sel_hi:[1,0]
	v_pk_mul_f32 v[62:63], v[38:39], v[134:135] op_sel_hi:[1,0]
	v_pk_mul_f32 v[64:65], v[40:41], v[134:135] op_sel_hi:[1,0]
	v_pk_mul_f32 v[80:81], v[80:81], v[100:101]
	v_pk_mul_f32 v[82:83], v[82:83], v[102:103]
	v_pk_mul_f32 v[62:63], v[62:63], v[104:105]
	v_pk_mul_f32 v[64:65], v[64:65], v[106:107]
	v_cvt_pk_bf16_f32 v76, v80, v81
	v_cvt_pk_bf16_f32 v77, v82, v83
	v_cvt_pk_bf16_f32 v78, v62, v63
	v_cvt_pk_bf16_f32 v79, v64, v65
	s_nop 1
	v_permlane32_swap_b32_e32 v76, v78
	v_permlane32_swap_b32_e32 v77, v79
	s_nop 0
	global_store_dwordx4 v[136:137], v[76:79], off offset:128
	v_pk_mul_f32 v[80:81], v[42:43], v[134:135] op_sel_hi:[1,0]
	v_pk_mul_f32 v[82:83], v[44:45], v[134:135] op_sel_hi:[1,0]
	v_pk_mul_f32 v[62:63], v[46:47], v[134:135] op_sel_hi:[1,0]
	v_pk_mul_f32 v[64:65], v[48:49], v[134:135] op_sel_hi:[1,0]
	v_pk_mul_f32 v[80:81], v[80:81], v[108:109]
	v_pk_mul_f32 v[82:83], v[82:83], v[110:111]
	v_pk_mul_f32 v[62:63], v[62:63], v[112:113]
	v_pk_mul_f32 v[64:65], v[64:65], v[114:115]
	v_cvt_pk_bf16_f32 v76, v80, v81
	v_cvt_pk_bf16_f32 v77, v82, v83
	v_cvt_pk_bf16_f32 v78, v62, v63
	v_cvt_pk_bf16_f32 v79, v64, v65
	s_nop 1
	v_permlane32_swap_b32_e32 v76, v78
	v_permlane32_swap_b32_e32 v77, v79
	s_nop 0
	global_store_dwordx4 v[136:137], v[76:79], off offset:160
	v_pk_mul_f32 v[80:81], v[18:19], v[134:135] op_sel_hi:[1,0]
	v_pk_mul_f32 v[82:83], v[20:21], v[134:135] op_sel_hi:[1,0]
	v_pk_mul_f32 v[62:63], v[22:23], v[134:135] op_sel_hi:[1,0]
	v_pk_mul_f32 v[64:65], v[24:25], v[134:135] op_sel_hi:[1,0]
	v_pk_mul_f32 v[80:81], v[80:81], v[116:117]
	v_pk_mul_f32 v[82:83], v[82:83], v[118:119]
	v_pk_mul_f32 v[62:63], v[62:63], v[120:121]
	v_pk_mul_f32 v[64:65], v[64:65], v[122:123]
	v_cvt_pk_bf16_f32 v76, v80, v81
	v_cvt_pk_bf16_f32 v77, v82, v83
	v_cvt_pk_bf16_f32 v78, v62, v63
	v_cvt_pk_bf16_f32 v79, v64, v65
	s_nop 1
	v_permlane32_swap_b32_e32 v76, v78
	v_permlane32_swap_b32_e32 v77, v79
	s_nop 0
	global_store_dwordx4 v[136:137], v[76:79], off offset:192
	v_pk_mul_f32 v[80:81], v[26:27], v[134:135] op_sel_hi:[1,0]
	v_pk_mul_f32 v[82:83], v[28:29], v[134:135] op_sel_hi:[1,0]
	v_pk_mul_f32 v[62:63], v[30:31], v[134:135] op_sel_hi:[1,0]
	v_pk_mul_f32 v[64:65], v[32:33], v[134:135] op_sel_hi:[1,0]
	v_pk_mul_f32 v[80:81], v[80:81], v[124:125]
	v_pk_mul_f32 v[82:83], v[82:83], v[126:127]
	v_pk_mul_f32 v[62:63], v[62:63], v[128:129]
	v_pk_mul_f32 v[64:65], v[64:65], v[130:131]
	v_cvt_pk_bf16_f32 v76, v80, v81
	v_cvt_pk_bf16_f32 v77, v82, v83
	v_cvt_pk_bf16_f32 v78, v62, v63
	v_cvt_pk_bf16_f32 v79, v64, v65
	s_nop 1
	v_permlane32_swap_b32_e32 v76, v78
	v_permlane32_swap_b32_e32 v77, v79
	s_nop 0
	global_store_dwordx4 v[136:137], v[76:79], off offset:224
	s_branch .LBB0_555
